# no grid barrier in front of the independent K_PP phases
# speedup vs baseline: 1.0057x; 1.0057x over previous
; __device__ __forceinline__ void xcd_barrier(const XcdBarrier& b) {
;     asm volatile("s_waitcnt vmcnt(0)" ::: "memory");
;     __syncthreads();
;     if (threadIdx.x == 0) {
;         unsigned* bar = b.bar;
;         __builtin_amdgcn_s_waitcnt(0);
;         unsigned nloc = b.st[0], nx = b.st[1];
;         if (nloc == 0u) { xcd_barrier_complete(bar, b.x, nloc, nx); b.st[0] = nloc; b.st[1] = nx; }
; __global__ void __launch_bounds__(512, 2) mega(Params P, int ph_lo, int ph_hi) {
;     ...
;     for (int ph = ph_lo; ph < ph_hi; ++ph) {
;         if (ph > ph_lo) xcd_barrier(bar);
;         run_phase(fresh_params(), ph, lds);
.LBB0_24:
	s_cmp_le_i32 s95, s82
	s_cbranch_scc1 .LBB0_78
	s_mov_b32 s0, 0x8010100
	s_mov_b32 s1, 0x40
	s_bitcmp1_b64 s[0:1], s95
	s_cbranch_scc1 .LBB0_78
	s_waitcnt vmcnt(0)
	s_barrier
	s_mov_b64 s[0:1], exec
	v_readlane_b32 s2, v254, 3
	v_readlane_b32 s3, v254, 4
	s_and_b64 s[2:3], s[0:1], s[2:3]
	s_mov_b64 exec, s[2:3]
	s_cbranch_execz .LBB0_77
	v_readlane_b32 s2, v255, 7
	s_waitcnt vmcnt(0) expcnt(0) lgkmcnt(0)
	s_nop 0
	v_mov_b32_e32 v0, s2
	ds_read_b32 v2, v0
	v_readlane_b32 s2, v255, 8
	s_waitcnt lgkmcnt(0)
	v_cmp_ne_u32_e32 vcc, 0, v2
	v_mov_b32_e32 v0, s2
	ds_read_b32 v0, v0
	s_cbranch_vccnz .LBB0_41
	s_load_dwordx2 s[2:3], s[50:51], 0x0
	s_load_dword s4, s[50:51], 0x8
	s_mov_b32 s9, 1
	s_waitcnt lgkmcnt(0)
	s_mul_i32 s8, s3, s2
	s_mul_i32 s8, s8, s4
	s_branch .LBB0_29
